# all 12 grid barriers: shorter protocol (XCD counter; last arriver of each XCD writes back L2 and bumps one top counter all blocks poll)
# speedup vs baseline: 1.0373x; 1.0081x over previous
.Lgs_census_done:
	v_min_u32_e32 v18, 1, v1
	v_min_u32_e32 v22, 1, v2
	v_add_u32_e32 v18, v18, v22
	v_min_u32_e32 v22, 1, v3
	v_add_u32_e32 v18, v18, v22
	v_min_u32_e32 v22, 1, v4
	v_add_u32_e32 v18, v18, v22
	v_min_u32_e32 v22, 1, v5
	v_add_u32_e32 v18, v18, v22
	v_min_u32_e32 v22, 1, v6
	v_add_u32_e32 v18, v18, v22
	v_min_u32_e32 v22, 1, v7
	v_add_u32_e32 v18, v18, v22
	v_min_u32_e32 v22, 1, v8
	v_add_u32_e32 v18, v18, v22
	v_min_u32_e32 v22, 1, v9
	v_add_u32_e32 v18, v18, v22
	v_min_u32_e32 v22, 1, v10
	v_add_u32_e32 v18, v18, v22
	v_min_u32_e32 v22, 1, v11
	v_add_u32_e32 v18, v18, v22
	v_min_u32_e32 v22, 1, v12
	v_add_u32_e32 v18, v18, v22
	v_min_u32_e32 v22, 1, v13
	v_add_u32_e32 v18, v18, v22
	v_min_u32_e32 v22, 1, v14
	v_add_u32_e32 v18, v18, v22
	v_min_u32_e32 v22, 1, v15
	v_add_u32_e32 v18, v18, v22
	v_min_u32_e32 v22, 1, v16
	v_add_u32_e32 v18, v18, v22
	v_max_u32_e32 v19, 1, v19
	v_max_u32_e32 v18, 1, v18
	v_mov_b32_e32 v22, 0x20ff0
	ds_write_b32 v22, v19
	v_mov_b32_e32 v22, 0x20ff4
	ds_write_b32 v22, v18
	s_waitcnt lgkmcnt(0)
	v_readlane_b32 s98, v248, 1
	v_readlane_b32 s99, v248, 2
	v_mov_b32_e32 v0, 0x20ff0
	ds_read2_b32 v[2:3], v0 offset1:1
	v_mov_b32_e32 v1, 1
	v_mov_b32_e32 v4, s97
	v_lshlrev_b32_e32 v4, 8, v4
	s_add_u32 s98, s98, 0x1000
	s_addc_u32 s99, s99, 0
	s_nop 2
	global_atomic_add v5, v4, v1, s[98:99] offset:1024 sc0
	s_waitcnt vmcnt(0) lgkmcnt(0)
	v_mul_u32_u24_e32 v2, 1, v2
	v_mul_u32_u24_e32 v3, 1, v3
	v_add_u32_e32 v5, 1, v5
	v_cmp_ne_u32_e32 vcc, v5, v2
	v_mov_b32_e32 v6, 0x2400
	s_cbranch_vccnz .Lxb0_poll
	buffer_wbl2 sc1
	s_waitcnt vmcnt(0)
	global_atomic_add v6, v1, s[98:99]
.Lxb0_poll:
	s_mov_b32 s100, 0
.Lxb0_spin:
	global_load_dword v7, v6, s[98:99] sc1
	s_waitcnt vmcnt(0)
	v_cmp_ge_u32_e32 vcc, v7, v3
	s_cbranch_vccnz .Lxb0_done
	s_sleep 1
	s_add_i32 s100, s100, 1
	s_cmp_lt_u32 s100, 0x40000
	s_cbranch_scc1 .Lxb0_spin

.LBB0_172:
	s_waitcnt vmcnt(0)
	s_barrier
	s_mov_b64 s[0:1], exec
	v_readlane_b32 s2, v248, 3
	v_readlane_b32 s3, v248, 4
	s_and_b64 s[2:3], s[0:1], s[2:3]
	s_mov_b64 exec, s[2:3]
	s_cbranch_execz .LBB0_224
	v_readlane_b32 s98, v248, 1
	v_readlane_b32 s99, v248, 2
	v_mov_b32_e32 v0, 0x20ff0
	ds_read2_b32 v[2:3], v0 offset1:1
	v_mov_b32_e32 v1, 1
	v_mov_b32_e32 v4, s97
	v_lshlrev_b32_e32 v4, 8, v4
	s_add_u32 s98, s98, 0x1000
	s_addc_u32 s99, s99, 0
	s_nop 2
	global_atomic_add v5, v4, v1, s[98:99] offset:1024 sc0
	s_waitcnt vmcnt(0) lgkmcnt(0)
	v_mul_u32_u24_e32 v2, 2, v2
	v_mul_u32_u24_e32 v3, 2, v3
	v_add_u32_e32 v5, 1, v5
	v_cmp_ne_u32_e32 vcc, v5, v2
	v_mov_b32_e32 v6, 0x2400
	s_cbranch_vccnz .Lxb1_poll
	buffer_wbl2 sc1
	s_waitcnt vmcnt(0)
	global_atomic_add v6, v1, s[98:99]

.Lxb1_done:
	buffer_inv sc1
	s_waitcnt vmcnt(0)
.LBB0_224:
	s_or_b64 exec, exec, s[0:1]
	s_add_u32 s18, s90, 0x48f0000
	s_addc_u32 s19, s91, 0
	s_add_u32 s48, s90, 0x60000
	s_addc_u32 s49, s91, 0
	v_mov_b32_e32 v8, v193
	s_cmpk_lt_i32 s6, 0x800
	s_waitcnt lgkmcnt(0)
	s_barrier
	s_cselect_b64 s[0:1], -1, 0
	s_cmpk_gt_i32 s6, 0x7ff
	v_readfirstlane_b32 s2, v8
	s_cbranch_scc1 .LBB0_227
	s_ashr_i32 s3, s6, 31
	s_lshr_b32 s3, s3, 29
	s_add_i32 s3, s6, s3
	s_and_b32 s4, s3, -8
	s_sub_i32 s7, s6, s4
	s_cmp_gt_i32 s7, -1
	s_cbranch_scc0 .LBB0_228
	s_lshl_b32 s8, s7, 8
	s_cbranch_execz .LBB0_229
	s_branch .LBB0_230

.LBB0_379:
	s_waitcnt vmcnt(0)
	s_waitcnt vmcnt(0)
	s_barrier
	s_mov_b64 s[0:1], exec
	v_readlane_b32 s2, v248, 3
	v_readlane_b32 s3, v248, 4
	s_and_b64 s[2:3], s[0:1], s[2:3]
	s_mov_b64 exec, s[2:3]
	s_cbranch_execz .LBB0_431
	v_readlane_b32 s98, v248, 1
	v_readlane_b32 s99, v248, 2
	v_mov_b32_e32 v0, 0x20ff0
	ds_read2_b32 v[2:3], v0 offset1:1
	v_mov_b32_e32 v1, 1
	v_mov_b32_e32 v4, s97
	v_lshlrev_b32_e32 v4, 8, v4
	s_add_u32 s98, s98, 0x1000
	s_addc_u32 s99, s99, 0
	s_nop 2
	global_atomic_add v5, v4, v1, s[98:99] offset:1024 sc0
	s_waitcnt vmcnt(0) lgkmcnt(0)
	v_mul_u32_u24_e32 v2, 3, v2
	v_mul_u32_u24_e32 v3, 3, v3
	v_add_u32_e32 v5, 1, v5
	v_cmp_ne_u32_e32 vcc, v5, v2
	v_mov_b32_e32 v6, 0x2400
	s_cbranch_vccnz .Lxb2_poll
	buffer_wbl2 sc1
	s_waitcnt vmcnt(0)
	global_atomic_add v6, v1, s[98:99]

.Lxb2_done:
	buffer_inv sc1
	s_waitcnt vmcnt(0)
.LBB0_431:
	s_or_b64 exec, exec, s[0:1]
	s_add_u32 s22, s90, 0x198f0000
	s_addc_u32 s23, s91, 0
	v_mov_b32_e32 v9, v193
	s_waitcnt lgkmcnt(0)
	s_barrier
	s_cmpk_gt_i32 s6, 0x7f
	v_readfirstlane_b32 s10, v9
	s_cbranch_scc1 .LBB0_447
	v_lshlrev_b32_e32 v0, 4, v9
	v_add_u32_e32 v1, 0x2000, v0
	v_ashrrev_i32_e32 v2, 31, v1
	v_lshrrev_b32_e32 v2, 22, v2
	v_add_u32_e32 v2, v1, v2
	v_ashrrev_i32_e32 v8, 10, v2
	v_mul_i32_i24_e32 v2, 0x400, v8
	v_sub_u32_e32 v1, v1, v2
	v_lshrrev_b32_e32 v2, 4, v1
	v_bitop3_b32 v1, v2, v1, 32 bitop3:0x6c
	v_ashrrev_i32_e32 v2, 31, v1
	v_lshrrev_b32_e32 v2, 26, v2
	v_add_u32_e32 v2, v1, v2
	v_lshlrev_b32_e32 v3, 3, v8
	v_ashrrev_i32_e32 v10, 6, v2
	v_and_b32_e32 v3, -16, v3
	v_add_u32_e32 v3, v10, v3
	v_and_b32_e32 v4, 3, v10
	s_mov_b32 s0, 0x3fffe0
	v_lshrrev_b32_e32 v5, 2, v3
	v_lshlrev_b32_e32 v6, 1, v3
	v_and_b32_e32 v2, 0xc0, v2
	v_and_or_b32 v4, v3, s0, v4
	v_and_b32_e32 v5, 4, v5
	v_and_b32_e32 v6, 24, v6
	v_sub_u32_e32 v1, v1, v2
	v_mov_b32_e32 v2, 1
	v_or3_b32 v4, v4, v5, v6
	v_lshlrev_b32_e32 v5, 5, v8
	v_ashrrev_i16_sdwa v1, v2, sext(v1) dst_sel:DWORD dst_unused:UNUSED_PAD src0_sel:DWORD src1_sel:BYTE_0
	v_and_b32_e32 v11, 32, v5
	v_bfe_i32 v12, v1, 0, 16
	s_movk_i32 s13, 0x300
	v_add_u32_e32 v1, v11, v12
	v_mul_lo_u32 v3, v3, s13
	v_lshlrev_b32_e32 v5, 1, v1
	v_add_lshl_u32 v130, v1, v3, 1
	v_bfe_i32 v1, v9, 27, 1
	v_lshrrev_b32_e32 v1, 22, v1
	v_add_u32_e32 v1, v0, v1
	v_and_b32_e32 v1, 0xfffffc00, v1
	v_sub_u32_e32 v0, v0, v1
	v_lshrrev_b32_e32 v1, 4, v0
	v_ashrrev_i32_e32 v3, 31, v9
	v_bitop3_b32 v0, v1, v0, 32 bitop3:0x6c
	v_lshrrev_b32_e32 v3, 26, v3
	v_ashrrev_i32_e32 v1, 31, v0
	v_add_u32_e32 v3, v9, v3
	v_lshrrev_b32_e32 v1, 26, v1
	v_ashrrev_i32_e32 v14, 6, v3
	v_add_u32_e32 v1, v0, v1
	v_lshlrev_b32_e32 v3, 3, v14
	v_ashrrev_i32_e32 v13, 6, v1
	v_and_b32_e32 v3, -16, v3
	s_add_u32 s2, s90, 0x3760000
	v_lshl_add_u32 v128, v4, 10, v5
	v_add_u32_e32 v3, v13, v3
	v_and_b32_e32 v4, 3, v13
	s_addc_u32 s3, s91, 0
	v_and_or_b32 v4, v3, s0, v4
	s_ashr_i32 s0, s6, 31
	s_lshr_b32 s0, s0, 30
	s_add_i32 s0, s6, s0
	s_ashr_i32 s8, s0, 2
	s_lshl_b32 s0, s6, 8
	s_and_b32 s51, s0, 0x300
	s_ashr_i32 s9, s8, 31
	s_lshl_b64 s[0:1], s[8:9], 11
	s_lshl_b32 s5, s51, 1
	s_or_b32 s0, s0, s5
	s_ashr_i32 s4, s10, 6
	v_lshrrev_b32_e32 v5, 2, v3
	v_lshlrev_b32_e32 v6, 1, v3
	v_and_b32_e32 v1, 0xc0, v1
	s_mulk_i32 s1, 0x300
	s_mul_hi_u32 s5, s0, 0x300
	s_ashr_i32 s11, s10, 8
	s_lshl_b32 s12, s4, 10
	v_and_b32_e32 v5, 4, v5
	v_and_b32_e32 v6, 24, v6
	v_sub_u32_e32 v0, v0, v1
	s_add_i32 s5, s5, s1
	s_mulk_i32 s0, 0x300
	v_or3_b32 v4, v4, v5, v6
	v_lshlrev_b32_e32 v5, 5, v14
	v_ashrrev_i16_sdwa v0, v2, sext(v0) dst_sel:DWORD dst_unused:UNUSED_PAD src0_sel:DWORD src1_sel:BYTE_0
	s_add_u32 s38, s26, s0
	v_and_b32_e32 v15, 32, v5
	v_bfe_i32 v16, v0, 0, 16
	s_addc_u32 s39, s27, s5
	s_lshl_b64 s[0:1], s[8:9], 18
	v_add_u32_e32 v0, v15, v16
	s_add_u32 s40, s2, s0
	v_lshlrev_b32_e32 v1, 1, v0
	s_addc_u32 s41, s3, s1
	s_add_i32 s7, s12, 0
	v_lshl_add_u32 v132, v4, 10, v1
	s_add_i32 m0, s7, 0x10000
	v_mul_lo_u32 v1, v3, s13
	global_load_lds_dwordx4 v132, s[40:41]
	s_add_i32 m0, s7, 0x12000
	s_add_u32 s0, s40, 0x20000
	global_load_lds_dwordx4 v128, s[40:41]
	s_addc_u32 s1, s41, 0
	s_add_i32 m0, s7, 0x14000
	s_add_i32 s33, s7, 0x2000
	global_load_lds_dwordx4 v132, s[0:1]
	s_add_i32 m0, s7, 0x16000
	v_add_lshl_u32 v134, v0, v1, 1
	global_load_lds_dwordx4 v128, s[0:1]
	s_mov_b32 m0, s7
	s_add_u32 s0, s38, 0x30000
	global_load_lds_dwordx4 v134, s[38:39]
	s_mov_b32 m0, s33
	s_addc_u32 s1, s39, 0
	s_add_i32 s34, s7, 0x4000
	global_load_lds_dwordx4 v130, s[38:39]
	s_mov_b32 m0, s34
	s_add_i32 s35, s7, 0x6000
	global_load_lds_dwordx4 v134, s[0:1]
	s_mov_b32 m0, s35
	v_mov_b32_e32 v137, 0
	global_load_lds_dwordx4 v130, s[0:1]
	v_mov_b32_e32 v133, v137
	v_mov_b32_e32 v129, v137
	v_mov_b32_e32 v135, v137
	v_mov_b32_e32 v131, v137
	s_cmp_eq_u32 s11, 1
	s_mov_b32 s48, 0
	v_lshl_add_u64 v[6:7], s[40:41], 0, v[132:133]
	v_lshl_add_u64 v[4:5], s[40:41], 0, v[128:129]
	v_lshl_add_u64 v[0:1], s[38:39], 0, v[134:135]
	s_cselect_b64 s[0:1], -1, 0
	s_cmp_lg_u32 s11, 1
	v_lshl_add_u64 v[2:3], s[38:39], 0, v[130:131]
	s_cbranch_scc1 .LBB0_434
	s_barrier

.LBB0_492:
	s_waitcnt vmcnt(0) lgkmcnt(0)
	s_barrier
	s_waitcnt vmcnt(0)
	s_barrier
	s_mov_b64 s[0:1], exec
	v_readlane_b32 s2, v248, 3
	v_readlane_b32 s3, v248, 4
	s_and_b64 s[2:3], s[0:1], s[2:3]
	s_mov_b64 exec, s[2:3]
	s_cbranch_execz .LBB0_544
	v_readlane_b32 s98, v248, 1
	v_readlane_b32 s99, v248, 2
	v_mov_b32_e32 v0, 0x20ff0
	ds_read2_b32 v[2:3], v0 offset1:1
	v_mov_b32_e32 v1, 1
	v_mov_b32_e32 v4, s97
	v_lshlrev_b32_e32 v4, 8, v4
	s_add_u32 s98, s98, 0x1000
	s_addc_u32 s99, s99, 0
	s_nop 2
	global_atomic_add v5, v4, v1, s[98:99] offset:1024 sc0
	s_waitcnt vmcnt(0) lgkmcnt(0)
	v_mul_u32_u24_e32 v2, 4, v2
	v_mul_u32_u24_e32 v3, 4, v3
	v_add_u32_e32 v5, 1, v5
	v_cmp_ne_u32_e32 vcc, v5, v2
	v_mov_b32_e32 v6, 0x2400
	s_cbranch_vccnz .Lxb3_poll
	buffer_wbl2 sc1
	s_waitcnt vmcnt(0)
	global_atomic_add v6, v1, s[98:99]

.Lxb3_done:
	buffer_inv sc1
	s_waitcnt vmcnt(0)
.LBB0_544:
	s_or_b64 exec, exec, s[0:1]
	s_waitcnt lgkmcnt(0)
	v_mov_b32_e32 v0, 0x6050400
	v_perm_b32 v0, s6, v193, v0
	v_and_b32_e32 v1, 0x300, v193
	v_mad_u64_u32 v[0:1], s[0:1], s92, v1, v[0:1]
	s_mov_b32 s2, 0x10000
	v_cmp_gt_i32_e32 vcc, s2, v0
	v_and_b32_e32 v192, 63, v193
	s_barrier
	s_and_saveexec_b64 s[0:1], vcc
	s_cbranch_execz .LBB0_551
	v_mov_b32_e32 v3, 0
	v_lshlrev_b32_e32 v2, 3, v192
	v_lshl_add_u64 v[4:5], s[90:91], 0, v[2:3]
	s_mov_b64 s[4:5], 0x3fe0000
	s_lshl_b32 s3, s92, 9
	v_lshl_add_u64 v[4:5], v[4:5], 0, s[4:5]
	s_mov_b64 s[4:5], 0
	s_movk_i32 s7, 0x4000
	s_movk_i32 s12, 0x3c0
	v_lshlrev_b32_e32 v6, 2, v192
	v_mov_b32_e32 v7, v3
	s_movk_i32 s13, 0x600
	v_mov_b64_e32 v[8:9], s[90:91]
	v_lshlrev_b32_e32 v10, 1, v192
	v_mov_b32_e32 v11, v3
	s_mov_b64 s[8:9], 0x88f0400
	s_movk_i32 s14, 0x1000
	s_movk_i32 s15, 0x2000
	s_movk_i32 s16, 0x3000
	s_movk_i32 s17, 0x5000
	s_movk_i32 s33, 0x6000
	s_movk_i32 s34, 0x7000
	s_mov_b32 s35, 0x8000
	s_mov_b32 s38, 0x9000
	s_mov_b32 s39, 0xa000
	s_mov_b32 s40, 0xb000
	s_mov_b32 s41, 0xc000
	s_mov_b32 s42, 0xd000
	s_mov_b32 s43, 0xe000
	s_mov_b32 s44, 0xf000
	s_mov_b32 s45, 0x17000
	s_mov_b32 s48, 0x16000
	s_mov_b32 s49, 0x15000
	s_mov_b32 s50, 0x14000
	s_mov_b32 s51, 0x13000
	s_mov_b32 s54, 0x12000
	s_mov_b32 s55, 0x11000
	s_mov_b32 s56, 0xffff
	s_branch .LBB0_547

.LBB0_589:
	s_waitcnt vmcnt(0)
	s_barrier
	s_and_saveexec_b64 s[0:1], s[80:81]
	s_cbranch_execz .LBB0_641
	v_readlane_b32 s98, v248, 1
	v_readlane_b32 s99, v248, 2
	v_mov_b32_e32 v0, 0x20ff0
	ds_read2_b32 v[2:3], v0 offset1:1
	v_mov_b32_e32 v1, 1
	v_mov_b32_e32 v4, s97
	v_lshlrev_b32_e32 v4, 8, v4
	s_add_u32 s98, s98, 0x1000
	s_addc_u32 s99, s99, 0
	s_nop 2
	global_atomic_add v5, v4, v1, s[98:99] offset:1024 sc0
	s_waitcnt vmcnt(0) lgkmcnt(0)
	v_mul_u32_u24_e32 v2, 5, v2
	v_mul_u32_u24_e32 v3, 5, v3
	v_add_u32_e32 v5, 1, v5
	v_cmp_ne_u32_e32 vcc, v5, v2
	v_mov_b32_e32 v6, 0x2400
	s_cbranch_vccnz .Lxb4_poll
	buffer_wbl2 sc1
	s_waitcnt vmcnt(0)
	global_atomic_add v6, v1, s[98:99]

.Lxb4_done:
	buffer_inv sc1
	s_waitcnt vmcnt(0)
.LBB0_641:
	s_or_b64 exec, exec, s[0:1]
	v_mov_b32_e32 v9, v193
	s_cmpk_lt_i32 s6, 0x100
	s_waitcnt lgkmcnt(0)
	s_barrier
	s_cselect_b64 s[0:1], -1, 0
	s_cmpk_gt_i32 s6, 0xff
	v_readfirstlane_b32 s3, v9
	s_cbranch_scc1 .LBB0_657
	v_lshlrev_b32_e32 v0, 4, v9
	v_add_u32_e32 v1, 0x2000, v0
	v_ashrrev_i32_e32 v2, 31, v1
	v_lshrrev_b32_e32 v2, 22, v2
	v_add_u32_e32 v2, v1, v2
	v_ashrrev_i32_e32 v8, 10, v2
	v_mul_i32_i24_e32 v2, 0x400, v8
	v_sub_u32_e32 v1, v1, v2
	v_lshrrev_b32_e32 v2, 4, v1
	v_bitop3_b32 v1, v2, v1, 32 bitop3:0x6c
	v_ashrrev_i32_e32 v2, 31, v1
	v_lshrrev_b32_e32 v2, 26, v2
	v_add_u32_e32 v2, v1, v2
	v_lshlrev_b32_e32 v3, 3, v8
	v_ashrrev_i32_e32 v10, 6, v2
	v_and_b32_e32 v3, -16, v3
	v_add_u32_e32 v3, v10, v3
	v_and_b32_e32 v4, 3, v10
	s_mov_b32 s2, 0xffffe0
	v_lshrrev_b32_e32 v5, 2, v3
	v_lshlrev_b32_e32 v6, 1, v3
	v_and_b32_e32 v2, 0xc0, v2
	v_and_or_b32 v4, v3, s2, v4
	v_and_b32_e32 v5, 4, v5
	v_and_b32_e32 v6, 24, v6
	v_sub_u32_e32 v1, v1, v2
	v_mov_b32_e32 v2, 1
	v_or3_b32 v4, v4, v5, v6
	v_lshlrev_b32_e32 v5, 5, v8
	v_ashrrev_i16_sdwa v1, v2, sext(v1) dst_sel:DWORD dst_unused:UNUSED_PAD src0_sel:DWORD src1_sel:BYTE_0
	s_movk_i32 s33, 0x300
	v_and_b32_e32 v11, 32, v5
	v_bfe_i32 v12, v1, 0, 16
	v_mul_u32_u24_e32 v4, 0x300, v4
	v_add_u32_e32 v1, v11, v12
	v_mul_lo_u32 v3, v3, s33
	v_add_lshl_u32 v128, v4, v1, 1
	v_add_lshl_u32 v130, v1, v3, 1
	v_bfe_i32 v1, v9, 27, 1
	v_lshrrev_b32_e32 v1, 22, v1
	v_add_u32_e32 v1, v0, v1
	v_and_b32_e32 v1, 0xfffffc00, v1
	v_sub_u32_e32 v0, v0, v1
	v_lshrrev_b32_e32 v1, 4, v0
	v_ashrrev_i32_e32 v3, 31, v9
	v_bitop3_b32 v0, v1, v0, 32 bitop3:0x6c
	v_lshrrev_b32_e32 v3, 26, v3
	v_ashrrev_i32_e32 v1, 31, v0
	v_add_u32_e32 v3, v9, v3
	v_lshrrev_b32_e32 v1, 26, v1
	v_ashrrev_i32_e32 v14, 6, v3
	v_add_u32_e32 v1, v0, v1
	v_lshlrev_b32_e32 v3, 3, v14
	s_add_u32 s66, s90, 0x1f60000
	v_ashrrev_i32_e32 v13, 6, v1
	v_and_b32_e32 v3, -16, v3
	s_addc_u32 s67, s91, 0
	v_add_u32_e32 v3, v13, v3
	v_and_b32_e32 v4, 3, v13
	s_ashr_i32 s9, s6, 31
	v_and_or_b32 v4, v3, s2, v4
	s_lshr_b32 s2, s6, 31
	s_lshr_b32 s9, s9, 29
	s_add_i32 s2, s6, s2
	s_add_i32 s9, s6, s9
	s_and_b32 s8, s2, 0xfffffe
	s_ashr_i32 s54, s9, 3
	s_lshl_b32 s2, s2, 7
	s_sub_i32 s8, s6, s8
	s_and_b32 s2, s2, 0x300
	s_ashr_i32 s55, s54, 31
	s_lshl_b32 s56, s8, 8
	s_lshl_b64 s[8:9], s[54:55], 11
	s_lshl_b32 s11, s2, 1
	s_or_b32 s8, s8, s11
	s_ashr_i32 s10, s3, 6
	s_mulk_i32 s9, 0x300
	s_mul_hi_u32 s11, s8, 0x300
	s_ashr_i32 s7, s3, 8
	s_lshl_b32 s68, s10, 10
	s_add_i32 s11, s11, s9
	s_mulk_i32 s8, 0x300
	s_add_u32 s58, s26, s8
	s_addc_u32 s59, s27, s11
	s_ashr_i32 s57, s56, 31
	s_lshl_b64 s[8:9], s[54:55], 10
	s_lshl_b64 s[30:31], s[56:57], 1
	s_add_u32 s8, s30, s8
	v_lshrrev_b32_e32 v5, 2, v3
	v_lshlrev_b32_e32 v6, 1, v3
	v_and_b32_e32 v1, 0xc0, v1
	s_addc_u32 s9, s31, s9
	v_and_b32_e32 v5, 4, v5
	v_and_b32_e32 v6, 24, v6
	v_sub_u32_e32 v0, v0, v1
	s_mulk_i32 s9, 0x300
	s_mul_hi_u32 s11, s8, 0x300
	v_or3_b32 v4, v4, v5, v6
	v_lshlrev_b32_e32 v5, 5, v14
	v_ashrrev_i16_sdwa v0, v2, sext(v0) dst_sel:DWORD dst_unused:UNUSED_PAD src0_sel:DWORD src1_sel:BYTE_0
	s_add_i32 s11, s11, s9
	s_mulk_i32 s8, 0x300
	v_and_b32_e32 v15, 32, v5
	v_bfe_i32 v16, v0, 0, 16
	s_add_u32 s60, s66, s8
	v_mul_u32_u24_e32 v4, 0x300, v4
	v_add_u32_e32 v0, v15, v16
	s_addc_u32 s61, s67, s11
	s_add_i32 s57, s68, 0
	v_add_lshl_u32 v132, v4, v0, 1
	s_add_i32 m0, s57, 0x10000
	v_mul_lo_u32 v1, v3, s33
	global_load_lds_dwordx4 v132, s[60:61]
	s_add_i32 m0, s57, 0x12000
	s_add_u32 s8, s60, 0x30000
	global_load_lds_dwordx4 v128, s[60:61]
	s_addc_u32 s9, s61, 0
	s_add_i32 m0, s57, 0x14000
	s_add_i32 s69, s57, 0x2000
	global_load_lds_dwordx4 v132, s[8:9]
	s_add_i32 m0, s57, 0x16000
	v_add_lshl_u32 v134, v0, v1, 1
	global_load_lds_dwordx4 v128, s[8:9]
	s_mov_b32 m0, s57
	s_add_u32 s8, s58, 0x30000
	global_load_lds_dwordx4 v134, s[58:59]
	s_mov_b32 m0, s69
	s_addc_u32 s9, s59, 0
	s_add_i32 s70, s57, 0x4000
	global_load_lds_dwordx4 v130, s[58:59]
	s_mov_b32 m0, s70
	s_add_i32 s71, s57, 0x6000
	global_load_lds_dwordx4 v134, s[8:9]
	s_mov_b32 m0, s71
	v_mov_b32_e32 v137, 0
	global_load_lds_dwordx4 v130, s[8:9]
	v_mov_b32_e32 v133, v137
	v_mov_b32_e32 v129, v137
	v_mov_b32_e32 v135, v137
	v_mov_b32_e32 v131, v137
	s_cmp_eq_u32 s7, 1
	s_mov_b32 s72, 0
	v_lshl_add_u64 v[6:7], s[60:61], 0, v[132:133]
	v_lshl_add_u64 v[4:5], s[60:61], 0, v[128:129]
	v_lshl_add_u64 v[0:1], s[58:59], 0, v[134:135]
	s_cselect_b64 s[8:9], -1, 0
	s_cmp_lg_u32 s7, 1
	v_lshl_add_u64 v[2:3], s[58:59], 0, v[130:131]
	s_cbranch_scc1 .LBB0_644
	s_barrier

.LBB0_657:
	s_waitcnt vmcnt(0)
	s_waitcnt vmcnt(0)
	s_barrier
	s_and_saveexec_b64 s[8:9], s[80:81]
	s_cbranch_execz .LBB0_709
	v_readlane_b32 s98, v248, 1
	v_readlane_b32 s99, v248, 2
	v_mov_b32_e32 v0, 0x20ff0
	ds_read2_b32 v[2:3], v0 offset1:1
	v_mov_b32_e32 v1, 1
	v_mov_b32_e32 v4, s97
	v_lshlrev_b32_e32 v4, 8, v4
	s_add_u32 s98, s98, 0x1000
	s_addc_u32 s99, s99, 0
	s_nop 2
	global_atomic_add v5, v4, v1, s[98:99] offset:1024 sc0
	s_waitcnt vmcnt(0) lgkmcnt(0)
	v_mul_u32_u24_e32 v2, 6, v2
	v_mul_u32_u24_e32 v3, 6, v3
	v_add_u32_e32 v5, 1, v5
	v_cmp_ne_u32_e32 vcc, v5, v2
	v_mov_b32_e32 v6, 0x2400
	s_cbranch_vccnz .Lxb5_poll
	buffer_wbl2 sc1
	s_waitcnt vmcnt(0)
	global_atomic_add v6, v1, s[98:99]

.Lxb5_done:
	buffer_inv sc1
	s_waitcnt vmcnt(0)
.LBB0_709:
	s_or_b64 exec, exec, s[8:9]
	s_add_u32 s26, s90, 0x68f0000
	v_mov_b32_e32 v8, v193
	s_waitcnt lgkmcnt(0)
	s_barrier
	s_addc_u32 s27, s91, 0
	s_andn2_b64 vcc, exec, s[0:1]
	v_readfirstlane_b32 s2, v8
	s_cbranch_vccnz .LBB0_733
	s_ashr_i32 s64, s6, 31
	s_lshr_b32 s0, s64, 29
	s_add_i32 s7, s6, s0
	s_and_b32 s0, s7, -8
	s_sub_i32 s8, s6, s0
	s_cmp_gt_i32 s8, -1
	s_cbranch_scc0 .LBB0_712
	s_lshl_b32 s3, s8, 5
	s_cbranch_execz .LBB0_713
	s_branch .LBB0_714

.LBB0_733:
	s_waitcnt vmcnt(0)
	s_barrier
	s_and_saveexec_b64 s[0:1], s[80:81]
	s_cbranch_execz .LBB0_785
	v_readlane_b32 s98, v248, 1
	v_readlane_b32 s99, v248, 2
	v_mov_b32_e32 v0, 0x20ff0
	ds_read2_b32 v[2:3], v0 offset1:1
	v_mov_b32_e32 v1, 1
	v_mov_b32_e32 v4, s97
	v_lshlrev_b32_e32 v4, 8, v4
	s_add_u32 s98, s98, 0x1000
	s_addc_u32 s99, s99, 0
	s_nop 2
	global_atomic_add v5, v4, v1, s[98:99] offset:1024 sc0
	s_waitcnt vmcnt(0) lgkmcnt(0)
	v_mul_u32_u24_e32 v2, 7, v2
	v_mul_u32_u24_e32 v3, 7, v3
	v_add_u32_e32 v5, 1, v5
	v_cmp_ne_u32_e32 vcc, v5, v2
	v_mov_b32_e32 v6, 0x2400
	s_cbranch_vccnz .Lxb6_poll
	buffer_wbl2 sc1
	s_waitcnt vmcnt(0)
	global_atomic_add v6, v1, s[98:99]

.Lxb6_done:
	buffer_inv sc1
	s_waitcnt vmcnt(0)
.LBB0_785:
	s_or_b64 exec, exec, s[0:1]
	v_mov_b32_e32 v8, v193
	s_waitcnt lgkmcnt(0)
	v_cndmask_b32_e64 v0, 0, 1, s[28:29]
	s_barrier
	v_cmp_ne_u32_e64 s[10:11], 1, v0
	s_andn2_b64 vcc, exec, s[28:29]
	v_readfirstlane_b32 s3, v8
	s_cbranch_vccnz .LBB0_788
	s_ashr_i32 s0, s6, 31
	s_lshr_b32 s0, s0, 29
	s_add_i32 s2, s6, s0
	s_and_b32 s0, s2, -8
	s_sub_i32 s4, s6, s0
	s_cmp_gt_i32 s4, -1
	s_cbranch_scc0 .LBB0_789
	s_lshl_b32 s5, s4, 6
	s_cbranch_execz .LBB0_790
	s_branch .LBB0_791

.LBB0_909:
	s_waitcnt vmcnt(0)
	s_barrier
	s_and_saveexec_b64 s[0:1], s[80:81]
	s_cbranch_execz .LBB0_961
	v_readlane_b32 s98, v248, 1
	v_readlane_b32 s99, v248, 2
	v_mov_b32_e32 v0, 0x20ff0
	ds_read2_b32 v[2:3], v0 offset1:1
	v_mov_b32_e32 v1, 1
	v_mov_b32_e32 v4, s97
	v_lshlrev_b32_e32 v4, 8, v4
	s_add_u32 s98, s98, 0x1000
	s_addc_u32 s99, s99, 0
	s_nop 2
	global_atomic_add v5, v4, v1, s[98:99] offset:1024 sc0
	s_waitcnt vmcnt(0) lgkmcnt(0)
	v_mul_u32_u24_e32 v2, 8, v2
	v_mul_u32_u24_e32 v3, 8, v3
	v_add_u32_e32 v5, 1, v5
	v_cmp_ne_u32_e32 vcc, v5, v2
	v_mov_b32_e32 v6, 0x2400
	s_cbranch_vccnz .Lxb7_poll
	buffer_wbl2 sc1
	s_waitcnt vmcnt(0)
	global_atomic_add v6, v1, s[98:99]

.Lxb7_done:
	buffer_inv sc1
	s_waitcnt vmcnt(0)
.LBB0_961:
	s_or_b64 exec, exec, s[0:1]
	v_mov_b32_e32 v8, v193
	s_waitcnt lgkmcnt(0)
	s_barrier
	s_and_b64 vcc, exec, s[10:11]
	v_readfirstlane_b32 s24, v8
	s_cbranch_vccnz .LBB0_985
	s_ashr_i32 s2, s6, 31
	s_lshr_b32 s0, s2, 29
	s_add_i32 s3, s6, s0
	s_and_b32 s0, s3, -8
	s_sub_i32 s5, s6, s0
	s_cmp_gt_i32 s5, -1
	s_cbranch_scc0 .LBB0_964
	s_lshl_b32 s4, s5, 6
	s_cbranch_execz .LBB0_965
	s_branch .LBB0_966

.LBB0_985:
	s_waitcnt vmcnt(0)
	s_barrier
	s_and_saveexec_b64 s[0:1], s[80:81]
	s_cbranch_execz .LBB0_1037
	v_readlane_b32 s98, v248, 1
	v_readlane_b32 s99, v248, 2
	v_mov_b32_e32 v0, 0x20ff0
	ds_read2_b32 v[2:3], v0 offset1:1
	v_mov_b32_e32 v1, 1
	v_mov_b32_e32 v4, s97
	v_lshlrev_b32_e32 v4, 8, v4
	s_add_u32 s98, s98, 0x1000
	s_addc_u32 s99, s99, 0
	s_nop 2
	global_atomic_add v5, v4, v1, s[98:99] offset:1024 sc0
	s_waitcnt vmcnt(0) lgkmcnt(0)
	v_mul_u32_u24_e32 v2, 9, v2
	v_mul_u32_u24_e32 v3, 9, v3
	v_add_u32_e32 v5, 1, v5
	v_cmp_ne_u32_e32 vcc, v5, v2
	v_mov_b32_e32 v6, 0x2400
	s_cbranch_vccnz .Lxb8_poll
	buffer_wbl2 sc1
	s_waitcnt vmcnt(0)
	global_atomic_add v6, v1, s[98:99]

.Lxb8_done:
	buffer_inv sc1
	s_waitcnt vmcnt(0)
.LBB0_1037:
	s_or_b64 exec, exec, s[0:1]
	s_waitcnt lgkmcnt(0)
	v_lshrrev_b32_e32 v0, 5, v193
	v_and_b32_e32 v0, 30, v0
	v_lshl_add_u32 v144, s6, 4, v0
	s_mov_b32 s0, 0x8000
	v_cmp_gt_i32_e64 s[4:5], s0, v144
	v_ashrrev_i32_e32 v145, 31, v144
	s_barrier
	s_and_saveexec_b64 s[24:25], s[4:5]
	s_cbranch_execz .LBB0_1040
	v_lshlrev_b32_e32 v16, 4, v192
	global_load_dwordx4 v[0:3], v16, s[46:47]
	global_load_dwordx4 v[4:7], v16, s[46:47] offset:1024
	global_load_dwordx4 v[8:11], v16, s[46:47] offset:2048
	global_load_dwordx4 v[12:15], v16, s[46:47] offset:3072
	v_mbcnt_hi_u32_b32 v16, -1, v226
	v_and_b32_e32 v17, 64, v16
	v_add_u32_e32 v17, 64, v17
	v_xor_b32_e32 v18, 1, v16
	v_cmp_lt_i32_e32 vcc, v18, v17
	s_lshl_b32 s26, s92, 4
	v_or_b32_e32 v22, 0x80, v192
	v_cndmask_b32_e32 v18, v16, v18, vcc
	v_lshlrev_b32_e32 v44, 2, v18
	v_xor_b32_e32 v18, 2, v16
	v_cmp_lt_i32_e32 vcc, v18, v17
	v_or_b32_e32 v24, 0xc0, v192
	s_mov_b64 s[0:1], 0x198f0e00
	v_cndmask_b32_e32 v18, v16, v18, vcc
	v_lshlrev_b32_e32 v45, 2, v18
	v_xor_b32_e32 v18, 4, v16
	v_cmp_lt_i32_e32 vcc, v18, v17
	s_ashr_i32 s27, s26, 31
	s_lshl_b64 s[28:29], s[26:27], 11
	v_cndmask_b32_e32 v18, v16, v18, vcc
	v_lshlrev_b32_e32 v46, 2, v18
	v_xor_b32_e32 v18, 8, v16
	v_cmp_lt_i32_e32 vcc, v18, v17
	s_mov_b64 s[30:31], 0
	s_mov_b64 s[36:37], 0x3000
	v_cndmask_b32_e32 v18, v16, v18, vcc
	v_lshlrev_b32_e32 v47, 2, v18
	v_xor_b32_e32 v18, 16, v16
	v_cmp_lt_i32_e32 vcc, v18, v17
	s_mov_b64 s[38:39], 0x4000
	v_lshlrev_b32_e32 v20, 4, v192
	v_cndmask_b32_e32 v18, v16, v18, vcc
	v_lshlrev_b32_e32 v48, 2, v18
	v_xor_b32_e32 v18, 32, v16
	v_cmp_lt_i32_e32 vcc, v18, v17
	v_mov_b32_e32 v17, 0
	v_lshlrev_b32_e32 v22, 4, v22
	v_cndmask_b32_e32 v16, v16, v18, vcc
	v_lshlrev_b64 v[18:19], 11, v[144:145]
	v_lshl_or_b32 v18, v192, 3, v18
	v_lshlrev_b32_e32 v49, 2, v16
	v_or_b32_e32 v16, 64, v192
	v_lshl_add_u64 v[18:19], s[90:91], 0, v[18:19]
	v_lshl_add_u64 v[18:19], v[18:19], 0, s[0:1]
	v_lshlrev_b32_e32 v16, 4, v16
	v_lshlrev_b32_e32 v24, 4, v24
	v_mov_b32_e32 v50, 0x358637bd
	s_mov_b32 s2, 0xf800000
	v_mov_b32_e32 v51, 0x260
	s_mov_b32 s3, 0xeb000000
	s_movk_i32 s7, 0x7fff
	v_mov_b32_e32 v21, v17
	v_mov_b32_e32 v52, v144

.LBB0_1040:
	s_or_b64 exec, exec, s[24:25]
	s_waitcnt vmcnt(0)
	s_barrier
	s_and_saveexec_b64 s[0:1], s[80:81]
	s_cbranch_execz .LBB0_1092
	v_readlane_b32 s98, v248, 1
	v_readlane_b32 s99, v248, 2
	v_mov_b32_e32 v0, 0x20ff0
	ds_read2_b32 v[2:3], v0 offset1:1
	v_mov_b32_e32 v1, 1
	v_mov_b32_e32 v4, s97
	v_lshlrev_b32_e32 v4, 8, v4
	s_add_u32 s98, s98, 0x1000
	s_addc_u32 s99, s99, 0
	s_nop 2
	global_atomic_add v5, v4, v1, s[98:99] offset:1024 sc0
	s_waitcnt vmcnt(0) lgkmcnt(0)
	v_mul_u32_u24_e32 v2, 10, v2
	v_mul_u32_u24_e32 v3, 10, v3
	v_add_u32_e32 v5, 1, v5
	v_cmp_ne_u32_e32 vcc, v5, v2
	v_mov_b32_e32 v6, 0x2400
	s_cbranch_vccnz .Lxb9_poll
	buffer_wbl2 sc1
	s_waitcnt vmcnt(0)
	global_atomic_add v6, v1, s[98:99]

.Lxb9_done:
	buffer_inv sc1
	s_waitcnt vmcnt(0)
.LBB0_1092:
	s_or_b64 exec, exec, s[0:1]
	v_mov_b32_e32 v10, v193
	s_waitcnt lgkmcnt(0)
	s_barrier
	s_cmpk_gt_i32 s6, 0xaff
	v_readfirstlane_b32 s0, v10
	s_cbranch_scc1 .LBB0_1108
	v_lshlrev_b32_e32 v0, 4, v10
	v_add_u32_e32 v1, 0x2000, v0
	v_ashrrev_i32_e32 v2, 31, v1
	v_lshrrev_b32_e32 v2, 22, v2
	v_add_u32_e32 v2, v1, v2
	v_ashrrev_i32_e32 v8, 10, v2
	v_mul_i32_i24_e32 v2, 0x400, v8
	v_sub_u32_e32 v1, v1, v2
	v_lshrrev_b32_e32 v2, 4, v1
	v_bitop3_b32 v1, v2, v1, 32 bitop3:0x6c
	v_ashrrev_i32_e32 v2, 31, v1
	v_lshrrev_b32_e32 v2, 26, v2
	v_add_u32_e32 v2, v1, v2
	v_lshlrev_b32_e32 v3, 3, v8
	v_ashrrev_i32_e32 v9, 6, v2
	v_and_b32_e32 v3, -16, v3
	v_add_u32_e32 v3, v9, v3
	v_and_b32_e32 v4, 3, v9
	s_mov_b32 s3, 0x1fffe0
	v_lshrrev_b32_e32 v5, 2, v3
	v_lshlrev_b32_e32 v6, 1, v3
	v_and_b32_e32 v2, 0xc0, v2
	v_and_or_b32 v4, v3, s3, v4
	v_and_b32_e32 v5, 4, v5
	v_and_b32_e32 v6, 24, v6
	v_sub_u32_e32 v1, v1, v2
	v_mov_b32_e32 v2, 1
	v_or3_b32 v4, v4, v5, v6
	v_lshlrev_b32_e32 v5, 5, v8
	v_ashrrev_i16_sdwa v1, v2, sext(v1) dst_sel:DWORD dst_unused:UNUSED_PAD src0_sel:DWORD src1_sel:BYTE_0
	v_and_b32_e32 v5, 32, v5
	v_bfe_i32 v11, v1, 0, 16
	v_add_lshl_u32 v1, v5, v11, 1
	v_lshl_add_u32 v128, v4, 11, v1
	v_lshl_add_u32 v130, v3, 11, v1
	v_bfe_i32 v1, v10, 27, 1
	v_lshrrev_b32_e32 v1, 22, v1
	v_add_u32_e32 v1, v0, v1
	v_and_b32_e32 v1, 0xfffffc00, v1
	v_sub_u32_e32 v0, v0, v1
	v_lshrrev_b32_e32 v1, 4, v0
	v_ashrrev_i32_e32 v3, 31, v10
	v_bitop3_b32 v0, v1, v0, 32 bitop3:0x6c
	v_lshrrev_b32_e32 v3, 26, v3
	v_ashrrev_i32_e32 v1, 31, v0
	v_add_u32_e32 v3, v10, v3
	v_lshrrev_b32_e32 v1, 26, v1
	v_ashrrev_i32_e32 v13, 6, v3
	v_add_u32_e32 v1, v0, v1
	v_lshlrev_b32_e32 v3, 3, v13
	v_ashrrev_i32_e32 v12, 6, v1
	v_and_b32_e32 v3, -16, v3
	v_add_u32_e32 v3, v12, v3
	v_and_b32_e32 v4, 3, v12
	v_and_or_b32 v4, v3, s3, v4
	s_ashr_i32 s3, s6, 31
	s_lshr_b32 s7, s3, 29
	s_add_i32 s7, s6, s7
	s_ashr_i32 s12, s0, 6
	s_ashr_i32 s8, s7, 3
	s_and_b32 s7, s7, -8
	s_ashr_i32 s1, s0, 8
	s_lshl_b32 s2, s12, 10
	s_sub_i32 s9, s6, s7
	s_cmp_lt_i32 s9, 0
	s_movk_i32 s7, 0x161
	s_cselect_b32 s13, s7, 0x160
	s_mul_i32 s9, s9, s13
	s_add_i32 s9, s9, s8
	s_mul_hi_i32 s8, s9, 0x2e8ba2e9
	s_lshr_b32 s13, s8, 31
	s_ashr_i32 s8, s8, 5
	s_add_i32 s8, s8, s13
	s_mul_i32 s13, s8, 0xb0
	s_sub_i32 s9, s9, s13
	s_sext_i32_i16 s13, s9
	s_bfe_u32 s13, s13, 0x3001c
	s_add_i32 s13, s9, s13
	s_sext_i32_i16 s24, s13
	s_and_b32 s13, s13, 0xfff8
	s_sub_i32 s9, s9, s13
	s_sext_i32_i16 s9, s9
	s_lshl_b32 s8, s8, 11
	s_lshl_b32 s9, s9, 8
	s_add_i32 s38, s9, s8
	s_lshl_b32 s8, s24, 5
	s_ashr_i32 s39, s38, 31
	s_and_b32 s40, s8, 0xffffff00
	s_lshl_b64 s[8:9], s[38:39], 11
	v_lshrrev_b32_e32 v5, 2, v3
	v_lshlrev_b32_e32 v6, 1, v3
	v_and_b32_e32 v1, 0xc0, v1
	s_add_u32 s42, s18, s8
	v_and_b32_e32 v5, 4, v5
	v_and_b32_e32 v6, 24, v6
	v_sub_u32_e32 v0, v0, v1
	s_addc_u32 s43, s19, s9
	s_ashr_i32 s41, s40, 31
	v_or3_b32 v4, v4, v5, v6
	v_lshlrev_b32_e32 v5, 5, v13
	v_ashrrev_i16_sdwa v0, v2, sext(v0) dst_sel:DWORD dst_unused:UNUSED_PAD src0_sel:DWORD src1_sel:BYTE_0
	s_lshl_b64 s[8:9], s[40:41], 11
	v_and_b32_e32 v5, 32, v5
	v_bfe_i32 v14, v0, 0, 16
	s_add_u32 s44, s16, s8
	v_add_lshl_u32 v0, v5, v14, 1
	s_addc_u32 s45, s17, s9
	s_add_i32 s33, s2, 0
	v_lshl_add_u32 v132, v4, 11, v0
	s_add_i32 m0, s33, 0x10000
	v_lshl_add_u32 v134, v3, 11, v0
	global_load_lds_dwordx4 v132, s[44:45]
	s_add_i32 m0, s33, 0x12000
	s_add_u32 s8, s44, 0x40000
	global_load_lds_dwordx4 v128, s[44:45]
	s_addc_u32 s9, s45, 0
	s_add_i32 m0, s33, 0x14000
	s_add_i32 s34, s33, 0x2000
	global_load_lds_dwordx4 v132, s[8:9]
	s_add_i32 m0, s33, 0x16000
	v_mov_b32_e32 v137, 0
	global_load_lds_dwordx4 v128, s[8:9]
	s_mov_b32 m0, s33
	s_add_u32 s8, s42, 0x40000
	global_load_lds_dwordx4 v134, s[42:43]
	s_mov_b32 m0, s34
	s_addc_u32 s9, s43, 0
	s_add_i32 s35, s33, 0x4000
	global_load_lds_dwordx4 v130, s[42:43]
	s_mov_b32 m0, s35
	s_add_i32 s39, s33, 0x6000
	global_load_lds_dwordx4 v134, s[8:9]
	s_mov_b32 m0, s39
	v_mov_b32_e32 v133, v137
	global_load_lds_dwordx4 v130, s[8:9]
	v_mov_b32_e32 v129, v137
	v_mov_b32_e32 v135, v137
	v_mov_b32_e32 v131, v137
	s_cmp_eq_u32 s1, 1
	s_mov_b32 s41, 0
	v_lshl_add_u64 v[6:7], s[44:45], 0, v[132:133]
	v_lshl_add_u64 v[4:5], s[44:45], 0, v[128:129]
	v_lshl_add_u64 v[0:1], s[42:43], 0, v[134:135]
	s_cselect_b64 s[8:9], -1, 0
	s_cmp_lg_u32 s1, 1
	v_lshl_add_u64 v[2:3], s[42:43], 0, v[130:131]
	s_cbranch_scc1 .LBB0_1095
	s_barrier

.LBB0_1108:
	s_waitcnt vmcnt(0)
	s_waitcnt vmcnt(0)
	s_barrier
	s_and_saveexec_b64 s[0:1], s[80:81]
	s_cbranch_execz .LBB0_1160
	v_readlane_b32 s98, v248, 1
	v_readlane_b32 s99, v248, 2
	v_mov_b32_e32 v0, 0x20ff0
	ds_read2_b32 v[2:3], v0 offset1:1
	v_mov_b32_e32 v1, 1
	v_mov_b32_e32 v4, s97
	v_lshlrev_b32_e32 v4, 8, v4
	s_add_u32 s98, s98, 0x1000
	s_addc_u32 s99, s99, 0
	s_nop 2
	global_atomic_add v5, v4, v1, s[98:99] offset:1024 sc0
	s_waitcnt vmcnt(0) lgkmcnt(0)
	v_mul_u32_u24_e32 v2, 11, v2
	v_mul_u32_u24_e32 v3, 11, v3
	v_add_u32_e32 v5, 1, v5
	v_cmp_ne_u32_e32 vcc, v5, v2
	v_mov_b32_e32 v6, 0x2400
	s_cbranch_vccnz .Lxb10_poll
	buffer_wbl2 sc1
	s_waitcnt vmcnt(0)
	global_atomic_add v6, v1, s[98:99]

.Lxb10_done:
	buffer_inv sc1
	s_waitcnt vmcnt(0)
.LBB0_1160:
	s_or_b64 exec, exec, s[0:1]
	s_waitcnt lgkmcnt(0)
	s_barrier
	s_and_b64 vcc, exec, s[10:11]
	v_readfirstlane_b32 s12, v193
	s_cbranch_vccnz .LBB0_1184
	s_ashr_i32 s2, s6, 31
	s_lshr_b32 s0, s2, 29
	s_add_i32 s8, s6, s0
	s_and_b32 s0, s8, -8
	s_sub_i32 s3, s6, s0
	s_cmp_gt_i32 s3, -1
	s_cbranch_scc0 .LBB0_1163
	s_lshl_b32 s7, s3, 6
	s_ashr_i32 s8, s8, 3
	s_cbranch_execz .LBB0_1164
	s_branch .LBB0_1165

.LBB0_1184:
	s_waitcnt vmcnt(0)
	s_barrier
	s_and_saveexec_b64 s[0:1], s[80:81]
	s_cbranch_execz .LBB0_1236
	v_readlane_b32 s98, v248, 1
	v_readlane_b32 s99, v248, 2
	v_mov_b32_e32 v0, 0x20ff0
	ds_read2_b32 v[2:3], v0 offset1:1
	v_mov_b32_e32 v1, 1
	v_mov_b32_e32 v4, s97
	v_lshlrev_b32_e32 v4, 8, v4
	s_add_u32 s98, s98, 0x1000
	s_addc_u32 s99, s99, 0
	s_nop 2
	global_atomic_add v5, v4, v1, s[98:99] offset:1024 sc0
	s_waitcnt vmcnt(0) lgkmcnt(0)
	v_mul_u32_u24_e32 v2, 12, v2
	v_mul_u32_u24_e32 v3, 12, v3
	v_add_u32_e32 v5, 1, v5
	v_cmp_ne_u32_e32 vcc, v5, v2
	v_mov_b32_e32 v6, 0x2400
	s_cbranch_vccnz .Lxb11_poll
	buffer_wbl2 sc1
	s_waitcnt vmcnt(0)
	global_atomic_add v6, v1, s[98:99]

.Lxb11_done:
	buffer_inv sc1
	s_waitcnt vmcnt(0)
.LBB0_1236:
	s_or_b64 exec, exec, s[0:1]
	s_waitcnt lgkmcnt(0)
	s_barrier
	s_and_saveexec_b64 s[0:1], s[4:5]
	s_cbranch_execz .LBB0_1239
	v_mbcnt_hi_u32_b32 v0, -1, v226
	v_and_b32_e32 v1, 64, v0
	v_add_u32_e32 v1, 64, v1
	v_xor_b32_e32 v2, 1, v0
	v_cmp_lt_i32_e32 vcc, v2, v1
	v_lshlrev_b64 v[4:5], 12, v[144:145]
	v_mov_b32_e32 v3, 0
	v_cndmask_b32_e32 v2, v0, v2, vcc
	v_lshlrev_b32_e32 v6, 2, v2
	v_xor_b32_e32 v2, 2, v0
	v_cmp_lt_i32_e32 vcc, v2, v1
	s_lshl_b32 s2, s92, 4
	s_mov_b64 s[0:1], 0x1000
	v_cndmask_b32_e32 v2, v0, v2, vcc
	v_lshlrev_b32_e32 v7, 2, v2
	v_xor_b32_e32 v2, 4, v0
	v_cmp_lt_i32_e32 vcc, v2, v1
	s_ashr_i32 s3, s2, 31
	s_lshl_b64 s[4:5], s[2:3], 12
	v_cndmask_b32_e32 v2, v0, v2, vcc
	v_lshlrev_b32_e32 v8, 2, v2
	v_xor_b32_e32 v2, 8, v0
	v_cmp_lt_i32_e32 vcc, v2, v1
	s_lshl_b64 s[6:7], s[2:3], 11
	s_mov_b64 s[8:9], 0
	v_cndmask_b32_e32 v2, v0, v2, vcc
	v_lshlrev_b32_e32 v9, 2, v2
	v_xor_b32_e32 v2, 16, v0
	v_cmp_lt_i32_e32 vcc, v2, v1
	v_mov_b32_e32 v12, 0x358637bd
	s_mov_b32 s3, 0xf800000
	v_cndmask_b32_e32 v2, v0, v2, vcc
	v_lshlrev_b32_e32 v10, 2, v2
	v_xor_b32_e32 v2, 32, v0
	v_cmp_lt_i32_e32 vcc, v2, v1
	v_mov_b32_e32 v13, 0x260
	s_movk_i32 s10, 0x7fff
	v_cndmask_b32_e32 v0, v0, v2, vcc
	v_lshlrev_b32_e32 v2, 4, v192
	v_or_b32_e32 v4, v4, v2
	v_lshlrev_b32_e32 v11, 2, v0
	v_lshl_add_u64 v[0:1], s[86:87], 0, v[2:3]
	v_lshl_add_u64 v[2:3], s[88:89], 0, v[4:5]
	v_lshlrev_b64 v[4:5], 11, v[144:145]
	v_lshl_or_b32 v4, v192, 3, v4
	v_lshl_add_u64 v[2:3], v[2:3], 0, s[0:1]
	v_lshl_add_u64 v[4:5], s[90:91], 0, v[4:5]
	s_mov_b64 s[0:1], 0x48f0000
	v_lshl_add_u64 v[4:5], v[4:5], 0, s[0:1]
